# v18 + LN1 router: expert-logit chunk sums fused onto the running sum (v_fma + 3 v_fmac instead of v_mul + 3 v_fmac + v_add), 59 of 64 groups per token
# baseline (speedup 1.0000x reference)
.LBB0_552:
	s_add_i32 s23, s7, 1
	s_waitcnt vmcnt(0)
	v_mov_b64_e32 v[38:39], v[84:85]
	v_mov_b64_e32 v[32:33], v[92:93]
	v_mov_b64_e32 v[34:35], v[90:91]
	v_mov_b64_e32 v[36:37], v[88:89]
	v_mov_b32_e32 v0, s23
	v_min_u32_e32 v0, 15, v0
	v_mov_b32_e32 v1, 0
	v_lshl_add_u64 v[0:1], v[82:83], 0, v[0:1]
	v_lshlrev_b64 v[2:3], 12, v[0:1]
	v_lshlrev_b64 v[0:1], 11, v[0:1]
	v_lshl_add_u64 v[12:13], v[62:63], 0, v[2:3]
	v_lshl_add_u64 v[92:93], v[64:65], 0, v[0:1]
	global_load_dwordx4 v[0:3], v[12:13], off
	global_load_dwordx2 v[84:85], v[92:93], off
	global_load_dwordx4 v[4:7], v[12:13], off offset:1024
	global_load_dwordx2 v[88:89], v[92:93], off offset:512
	global_load_dwordx4 v[8:11], v[12:13], off offset:2048
	global_load_dwordx2 v[90:91], v[92:93], off offset:1024
	s_nop 0
	global_load_dwordx4 v[12:15], v[12:13], off offset:3072
	s_nop 0
	global_load_dwordx2 v[92:93], v[92:93], off offset:1536
	v_lshlrev_b32_e32 v40, 16, v38
	v_and_b32_e32 v41, 0xffff0000, v38
	v_lshlrev_b32_e32 v38, 16, v39
	v_and_b32_e32 v39, 0xffff0000, v39
	v_lshlrev_b32_e32 v54, 16, v36
	v_and_b32_e32 v55, 0xffff0000, v36
	v_lshlrev_b32_e32 v94, 16, v37
	v_and_b32_e32 v95, 0xffff0000, v37
	v_lshlrev_b32_e32 v96, 16, v34
	v_and_b32_e32 v97, 0xffff0000, v34
	v_lshlrev_b32_e32 v100, 16, v35
	v_and_b32_e32 v101, 0xffff0000, v35
	v_lshlrev_b32_e32 v102, 16, v32
	v_and_b32_e32 v103, 0xffff0000, v32
	v_lshlrev_b32_e32 v104, 16, v33
	v_and_b32_e32 v105, 0xffff0000, v33
	v_pk_fma_f32 v[106:107], v[30:31], s[22:23], v[38:39] op_sel_hi:[1,0,1]
	ds_read_b128 v[30:33], v234
	ds_read_b128 v[34:37], v234 offset:4096
	v_pk_fma_f32 v[28:29], v[28:29], s[22:23], v[40:41] op_sel_hi:[1,0,1]
	v_pk_fma_f32 v[20:21], v[20:21], s[22:23], v[54:55] op_sel_hi:[1,0,1]
	v_add_f32_e32 v38, v28, v29
	v_add_f32_e32 v38, v38, v106
	v_pk_fma_f32 v[22:23], v[22:23], s[22:23], v[94:95] op_sel_hi:[1,0,1]
	v_add_f32_e32 v54, v20, v21
	v_pk_fma_f32 v[24:25], v[24:25], s[22:23], v[96:97] op_sel_hi:[1,0,1]
	v_add_f32_e32 v38, v107, v38
	v_add_f32_e32 v54, v54, v22
	v_pk_fma_f32 v[26:27], v[26:27], s[22:23], v[100:101] op_sel_hi:[1,0,1]
	v_add_f32_e32 v55, v24, v25
	v_add_f32_e32 v98, 0, v38
	v_add_f32_e32 v54, v23, v54
	v_add_f32_e32 v55, v55, v26
	v_add_f32_e32 v54, v98, v54
	v_add_f32_e32 v55, v27, v55
	v_pk_fma_f32 v[16:17], v[16:17], s[22:23], v[102:103] op_sel_hi:[1,0,1]
	v_add_f32_e32 v54, v54, v55
	v_pk_fma_f32 v[18:19], v[18:19], s[22:23], v[104:105] op_sel_hi:[1,0,1]
	v_add_f32_e32 v55, v16, v17
	v_add_f32_e32 v55, v55, v18
	v_add_f32_e32 v55, v19, v55
	v_add_f32_e32 v54, v54, v55
	ds_read_b128 v[38:41], v60
	ds_read_b128 v[42:45], v60 offset:4096
	ds_read_b128 v[46:49], v60 offset:8192
	ds_read_b128 v[50:53], v60 offset:12288
	ds_read_b128 v[108:111], v60 offset:16384
	ds_read_b128 v[122:125], v60 offset:20480
	ds_read_b128 v[130:133], v60 offset:24576
	ds_read_b128 v[134:137], v60 offset:28672
	ds_read_b128 v[138:141], v60 offset:32768
	ds_read_b128 v[142:145], v60 offset:36864
	ds_read_b128 v[146:149], v60 offset:40960
	ds_read_b128 v[150:153], v60 offset:45056
	ds_read_b128 v[154:157], v60 offset:49152
	v_add_f32_dpp v54, v54, v54 quad_perm:[1,0,3,2] row_mask:0xf bank_mask:0xf bound_ctrl:1
	s_nop 1
	v_add_f32_dpp v54, v54, v54 quad_perm:[2,3,0,1] row_mask:0xf bank_mask:0xf bound_ctrl:1
	s_nop 1
	v_add_f32_dpp v54, v54, v54 row_half_mirror row_mask:0xf bank_mask:0xf bound_ctrl:1
	s_nop 1
	v_add_f32_dpp v54, v54, v54 row_mirror row_mask:0xf bank_mask:0xf bound_ctrl:1
	s_nop 0
	v_readlane_b32 s2, v54, 16
	v_readlane_b32 s4, v54, 48
	v_readlane_b32 s0, v54, 0
	v_readlane_b32 s1, v54, 32
	v_mov_b32_e32 v54, s2
	v_mov_b32_e32 v55, s4
	v_pk_add_f32 v[54:55], s[0:1], v[54:55]
	s_nop 0
	v_add_f32_e32 v54, v54, v55
	v_mul_f32_e32 v54, 0x3a800000, v54
	v_pk_add_f32 v[28:29], v[28:29], v[54:55] op_sel_hi:[1,0] neg_lo:[0,1] neg_hi:[0,1]
	v_pk_add_f32 v[126:127], v[106:107], v[54:55] op_sel_hi:[1,0] neg_lo:[0,1] neg_hi:[0,1]
	v_pk_mul_f32 v[104:105], v[28:29], v[28:29]
	v_pk_mul_f32 v[106:107], v[126:127], v[126:127]
	v_pk_add_f32 v[158:159], v[20:21], v[54:55] op_sel_hi:[1,0] neg_lo:[0,1] neg_hi:[0,1]
	v_pk_add_f32 v[160:161], v[22:23], v[54:55] op_sel_hi:[1,0] neg_lo:[0,1] neg_hi:[0,1]
	v_pk_add_f32 v[100:101], v[24:25], v[54:55] op_sel_hi:[1,0] neg_lo:[0,1] neg_hi:[0,1]
	v_pk_add_f32 v[102:103], v[26:27], v[54:55] op_sel_hi:[1,0] neg_lo:[0,1] neg_hi:[0,1]
	v_pk_add_f32 v[94:95], v[16:17], v[54:55] op_sel_hi:[1,0] neg_lo:[0,1] neg_hi:[0,1]
	v_pk_add_f32 v[96:97], v[18:19], v[54:55] op_sel_hi:[1,0] neg_lo:[0,1] neg_hi:[0,1]
	v_add_f32_e32 v54, v104, v105
	v_add_f32_e32 v54, v106, v54
	v_pk_mul_f32 v[20:21], v[158:159], v[158:159]
	v_add_f32_e32 v54, v107, v54
	v_add_f32_e32 v20, v20, v54
	v_pk_mul_f32 v[22:23], v[160:161], v[160:161]
	v_add_f32_e32 v20, v21, v20
	v_add_f32_e32 v20, v22, v20
	v_pk_mul_f32 v[24:25], v[100:101], v[100:101]
	v_add_f32_e32 v20, v23, v20
	v_add_f32_e32 v20, v24, v20
	v_pk_mul_f32 v[26:27], v[102:103], v[102:103]
	v_add_f32_e32 v20, v25, v20
	v_add_f32_e32 v20, v26, v20
	v_pk_mul_f32 v[16:17], v[94:95], v[94:95]
	v_add_f32_e32 v20, v27, v20
	v_add_f32_e32 v16, v16, v20
	v_pk_mul_f32 v[18:19], v[96:97], v[96:97]
	v_add_f32_e32 v16, v17, v16
	v_add_f32_e32 v16, v18, v16
	v_add_f32_e32 v16, v19, v16
	s_nop 1
	v_add_f32_dpp v16, v16, v16 quad_perm:[1,0,3,2] row_mask:0xf bank_mask:0xf bound_ctrl:1
	s_nop 1
	v_add_f32_dpp v16, v16, v16 quad_perm:[2,3,0,1] row_mask:0xf bank_mask:0xf bound_ctrl:1
	s_nop 1
	v_add_f32_dpp v16, v16, v16 row_half_mirror row_mask:0xf bank_mask:0xf bound_ctrl:1
	s_nop 1
	v_add_f32_dpp v16, v16, v16 row_mirror row_mask:0xf bank_mask:0xf bound_ctrl:1
	s_nop 0
	v_readlane_b32 s2, v16, 16
	v_readlane_b32 s4, v16, 48
	v_readlane_b32 s0, v16, 0
	v_readlane_b32 s1, v16, 32
	v_mov_b32_e32 v16, s2
	v_mov_b32_e32 v17, s4
	v_pk_add_f32 v[16:17], s[0:1], v[16:17]
	s_mov_b32 s0, 0x800000
	v_add_f32_e32 v16, v16, v17
	v_fmamk_f32 v16, v16, 0x3a800000, v116
	v_cmp_gt_f32_e32 vcc, s0, v16
	v_mul_f32_e32 v17, 0x4b800000, v16
	s_nop 0
	v_cndmask_b32_e32 v16, v16, v17, vcc
	v_rsq_f32_e32 v54, v16
	ds_read_b128 v[16:19], v60 offset:53248
	s_waitcnt lgkmcnt(15)
	ds_read_b128 v[20:23], v60 offset:57344
	s_waitcnt lgkmcnt(15)
	ds_read_b128 v[24:27], v60 offset:61440
	s_waitcnt lgkmcnt(15)
	v_mul_f32_e32 v55, 0x45800000, v54
	v_cndmask_b32_e32 v98, v54, v55, vcc
	v_pk_mul_f32 v[28:29], v[28:29], v[98:99] op_sel_hi:[1,0]
	v_pk_fma_f32 v[106:107], v[30:31], v[28:29], v[34:35]
	v_pk_mul_f32 v[28:29], v[126:127], v[98:99] op_sel_hi:[1,0]
	s_waitcnt lgkmcnt(2)
	v_mul_f32_e32 v17, v107, v17
	v_pk_fma_f32 v[104:105], v[32:33], v[28:29], v[36:37]
	v_cvt_pk_bf16_f32 v28, v106, v107
	v_cvt_pk_bf16_f32 v29, v104, v105
	global_store_dwordx2 v[86:87], v[28:29], off offset:-1024
	v_mul_f32_e32 v54, v39, v107
	v_fmac_f32_e32 v54, v38, v106
	ds_read_b128 v[32:35], v234 offset:1024
	ds_read_b128 v[36:39], v234 offset:5120
	v_fmac_f32_e32 v54, v104, v40
	v_fmac_f32_e32 v54, v105, v41
	v_mul_f32_e32 v55, v107, v43
	v_fmac_f32_e32 v55, v106, v42
	v_fmac_f32_e32 v55, v104, v44
	v_fmac_f32_e32 v55, v105, v45
	v_mul_f32_e32 v28, v107, v47
	v_fmac_f32_e32 v28, v106, v46
	v_fmac_f32_e32 v28, v104, v48
	v_fmac_f32_e32 v28, v105, v49
	v_add_f32_e32 v46, 0, v28
	v_mul_f32_e32 v45, v107, v51
	v_fmac_f32_e32 v45, v106, v50
	v_fmac_f32_e32 v45, v104, v52
	v_fmac_f32_e32 v45, v105, v53
	v_mul_f32_e32 v44, v107, v109
	v_fmac_f32_e32 v44, v106, v108
	v_fmac_f32_e32 v44, v104, v110
	v_fmac_f32_e32 v44, v105, v111
	v_mul_f32_e32 v53, v107, v123
	v_fmac_f32_e32 v53, v106, v122
	v_fmac_f32_e32 v53, v104, v124
	v_fmac_f32_e32 v53, v105, v125
	v_mul_f32_e32 v52, v107, v131
	v_fmac_f32_e32 v52, v106, v130
	v_fmac_f32_e32 v52, v104, v132
	v_fmac_f32_e32 v52, v105, v133
	v_mul_f32_e32 v51, v107, v135
	v_fmac_f32_e32 v51, v106, v134
	v_fmac_f32_e32 v51, v104, v136
	v_fmac_f32_e32 v51, v105, v137
	v_mul_f32_e32 v50, v107, v139
	v_fmac_f32_e32 v50, v106, v138
	v_fmac_f32_e32 v50, v104, v140
	v_fmac_f32_e32 v50, v105, v141
	v_mul_f32_e32 v49, v107, v143
	v_fmac_f32_e32 v49, v106, v142
	v_fmac_f32_e32 v49, v104, v144
	v_fmac_f32_e32 v49, v105, v145
	v_mul_f32_e32 v48, v107, v147
	v_fmac_f32_e32 v48, v106, v146
	v_fmac_f32_e32 v48, v104, v148
	v_fmac_f32_e32 v48, v105, v149
	v_mul_f32_e32 v131, v107, v151
	v_fmac_f32_e32 v17, v106, v16
	s_waitcnt lgkmcnt(3)
	v_mul_f32_e32 v122, v107, v21
	v_fmac_f32_e32 v131, v106, v150
	v_fmac_f32_e32 v122, v106, v20
	v_fmac_f32_e32 v131, v104, v152
	v_fmac_f32_e32 v122, v104, v22
	v_fmac_f32_e32 v131, v105, v153
	v_fmac_f32_e32 v122, v105, v23
	v_mul_f32_e32 v125, v107, v155
	s_waitcnt lgkmcnt(2)
	v_mul_f32_e32 v123, v107, v25
	v_fmac_f32_e32 v125, v106, v154
	v_fmac_f32_e32 v123, v106, v24
	v_fmac_f32_e32 v125, v104, v156
	v_fmac_f32_e32 v17, v104, v18
	v_fmac_f32_e32 v123, v104, v26
	v_fmac_f32_e32 v125, v105, v157
	v_fmac_f32_e32 v17, v105, v19
	v_fmac_f32_e32 v123, v105, v27
	v_pk_mul_f32 v[40:41], v[158:159], v[98:99] op_sel_hi:[1,0]
	v_add_f32_e32 v124, 0, v17
	s_waitcnt lgkmcnt(0)
	v_pk_fma_f32 v[108:109], v[40:41], v[32:33], v[36:37]
	ds_read_b128 v[40:43], v60 offset:1024
	ds_read_b128 v[134:137], v60 offset:21504
	v_pk_mul_f32 v[32:33], v[160:161], v[98:99] op_sel_hi:[1,0]
	ds_read_b128 v[142:145], v60 offset:29696
	v_pk_fma_f32 v[110:111], v[32:33], v[34:35], v[38:39]
	s_waitcnt lgkmcnt(2)
	v_fma_f32 v126, v109, v41, v54
	v_cvt_pk_bf16_f32 v32, v108, v109
	v_cvt_pk_bf16_f32 v33, v110, v111
	v_fmac_f32_e32 v126, v108, v40
	global_store_dwordx2 v[86:87], v[32:33], off offset:-512
	ds_read_b128 v[32:35], v60 offset:5120
	v_fmac_f32_e32 v126, v110, v42
	v_fmac_f32_e32 v126, v111, v43
	s_waitcnt lgkmcnt(2)
	v_fma_f32 v133, v109, v135, v53
	s_waitcnt lgkmcnt(1)
	v_fma_f32 v135, v109, v143, v51
	v_fmac_f32_e32 v135, v108, v142
	v_fmac_f32_e32 v135, v110, v144
	v_fmac_f32_e32 v135, v111, v145
	ds_read_b128 v[144:147], v60 offset:50176
	s_waitcnt lgkmcnt(1)
	v_fma_f32 v127, v109, v33, v55
	v_fmac_f32_e32 v127, v108, v32
	v_fmac_f32_e32 v127, v110, v34
	v_fmac_f32_e32 v127, v111, v35
	ds_read_b128 v[36:39], v60 offset:9216
	ds_read_b128 v[32:35], v60 offset:13312
	ds_read_b128 v[40:43], v60 offset:17408
	ds_read_b128 v[138:141], v60 offset:25600
	v_fmac_f32_e32 v133, v108, v134
	v_fmac_f32_e32 v133, v110, v136
	s_waitcnt lgkmcnt(3)
	v_fma_f32 v129, v109, v37, v46
	s_waitcnt lgkmcnt(2)
	v_fma_f32 v130, v109, v33, v45
	v_fmac_f32_e32 v133, v111, v137
	v_fmac_f32_e32 v129, v108, v36
	v_fmac_f32_e32 v130, v108, v32
	s_waitcnt lgkmcnt(0)
	v_fma_f32 v134, v109, v139, v52
	v_fmac_f32_e32 v129, v110, v38
	v_fmac_f32_e32 v130, v110, v34
	v_fma_f32 v132, v109, v41, v44
	v_fmac_f32_e32 v134, v108, v138
	v_fmac_f32_e32 v129, v111, v39
	v_fmac_f32_e32 v130, v111, v35
	v_fmac_f32_e32 v132, v108, v40
	v_fmac_f32_e32 v134, v110, v140
	v_fmac_f32_e32 v132, v110, v42
	v_fmac_f32_e32 v134, v111, v141
	v_fmac_f32_e32 v132, v111, v43
	ds_read_b128 v[52:55], v60 offset:33792
	ds_read_b128 v[138:141], v60 offset:37888
	s_waitcnt lgkmcnt(1)
	v_fma_f32 v136, v109, v53, v50
	v_fmac_f32_e32 v136, v108, v52
	v_fmac_f32_e32 v136, v110, v54
	v_fmac_f32_e32 v136, v111, v55
	ds_read_b128 v[50:53], v60 offset:41984
	s_waitcnt lgkmcnt(1)
	v_fma_f32 v137, v109, v139, v49
	v_fmac_f32_e32 v137, v108, v138
	v_fmac_f32_e32 v137, v110, v140
	v_fmac_f32_e32 v137, v111, v141
	ds_read_b128 v[140:143], v60 offset:46080
	s_waitcnt lgkmcnt(1)
	v_fma_f32 v138, v109, v51, v48
	v_fmac_f32_e32 v138, v108, v50
	v_fmac_f32_e32 v138, v110, v52
	v_fmac_f32_e32 v138, v111, v53
	ds_read_b128 v[48:51], v234 offset:2048
	ds_read_b128 v[52:55], v234 offset:6144
	s_waitcnt lgkmcnt(2)
	v_fma_f32 v131, v109, v141, v131
	v_fmac_f32_e32 v131, v108, v140
	v_fmac_f32_e32 v131, v110, v142
	v_fmac_f32_e32 v131, v111, v143
	ds_read_b128 v[140:143], v60 offset:54272
	v_fma_f32 v139, v109, v145, v125
	v_fmac_f32_e32 v139, v108, v144
	v_fmac_f32_e32 v139, v110, v146
	v_fmac_f32_e32 v139, v111, v147
	ds_read_b128 v[144:147], v60 offset:58368
	s_waitcnt lgkmcnt(1)
	v_fma_f32 v148, v109, v141, v124
	v_fmac_f32_e32 v148, v108, v140
	v_fmac_f32_e32 v148, v110, v142
	v_fmac_f32_e32 v148, v111, v143
	ds_read_b128 v[140:143], v60 offset:62464
	s_waitcnt lgkmcnt(1)
	v_mul_f32_e32 v124, v109, v145
	v_fmac_f32_e32 v124, v108, v144
	v_fmac_f32_e32 v124, v110, v146
	v_fmac_f32_e32 v124, v111, v147
	v_add_f32_e32 v144, v122, v124
	s_waitcnt lgkmcnt(0)
	v_mul_f32_e32 v122, v109, v141
	v_fmac_f32_e32 v122, v108, v140
	v_fmac_f32_e32 v122, v110, v142
	v_fmac_f32_e32 v122, v111, v143
	v_add_f32_e32 v142, v123, v122
	v_mov_b32_e32 v122, v106
	v_mov_b32_e32 v123, v108
	v_mov_b32_e32 v108, v107
	v_mov_b32_e32 v106, v186
	v_mov_b32_e32 v124, v182
	v_mov_b32_e32 v140, v190
	v_mov_b32_e32 v125, v198
	v_mov_b32_e32 v107, v202
	v_pk_mul_f32 v[106:107], v[108:109], v[106:107]
	v_mov_b32_e32 v36, v187
	v_pk_fma_f32 v[106:107], v[122:123], v[124:125], v[106:107]
	v_mov_b32_e32 v124, v104
	v_mov_b32_e32 v125, v110
	v_mov_b32_e32 v110, v105
	v_mov_b32_e32 v104, v194
	v_mov_b32_e32 v141, v206
	v_pk_fma_f32 v[106:107], v[124:125], v[140:141], v[106:107]
	v_mov_b32_e32 v105, v210
	v_mov_b32_e32 v32, v183
	v_mov_b32_e32 v37, v203
	v_pk_mul_f32 v[24:25], v[108:109], v[36:37]
	v_pk_fma_f32 v[104:105], v[110:111], v[104:105], v[106:107]
	v_mov_b32_e32 v33, v199
	v_pk_fma_f32 v[24:25], v[122:123], v[32:33], v[24:25]
	v_mov_b32_e32 v40, v191
	v_add_f32_e32 v16, 0, v104
	v_mov_b32_e32 v41, v207
	v_pk_fma_f32 v[20:21], v[124:125], v[40:41], v[24:25]
	v_mov_b32_e32 v44, v195
	v_add_f32_e32 v107, v16, v105
	v_mov_b32_e32 v45, v211
	v_pk_fma_f32 v[16:17], v[110:111], v[44:45], v[20:21]
	v_mov_b32_e32 v20, v188
	v_add_f32_e32 v16, 0, v16
	v_mov_b32_e32 v21, v204
	v_add_f32_e32 v105, v16, v17
	v_mov_b32_e32 v16, v184
	v_mov_b32_e32 v17, v200
	v_pk_mul_f32 v[20:21], v[108:109], v[20:21]
	v_mov_b32_e32 v38, v189
	v_pk_fma_f32 v[16:17], v[122:123], v[16:17], v[20:21]
	v_mov_b32_e32 v20, v192
	v_mov_b32_e32 v21, v208
	v_pk_fma_f32 v[16:17], v[124:125], v[20:21], v[16:17]
	v_mov_b32_e32 v20, v196
	v_mov_b32_e32 v21, v212
	v_pk_fma_f32 v[16:17], v[110:111], v[20:21], v[16:17]
	v_mov_b32_e32 v34, v185
	v_add_f32_e32 v16, 0, v16
	v_add_f32_e32 v106, v16, v17
	v_mov_b32_e32 v39, v205
	v_pk_mul_f32 v[16:17], v[108:109], v[38:39]
	v_mov_b32_e32 v42, v193
	v_mov_b32_e32 v35, v201
	v_pk_fma_f32 v[16:17], v[122:123], v[34:35], v[16:17]
	v_mov_b32_e32 v46, v197
	v_mov_b32_e32 v43, v209
	v_pk_fma_f32 v[16:17], v[124:125], v[42:43], v[16:17]
	v_pk_mul_f32 v[20:21], v[102:103], v[98:99] op_sel_hi:[1,0]
	v_mov_b32_e32 v47, v213
	v_pk_fma_f32 v[16:17], v[110:111], v[46:47], v[16:17]
	v_pk_fma_f32 v[50:51], v[20:21], v[50:51], v[54:55]
	v_add_f32_e32 v16, 0, v16
	v_add_f32_e32 v104, v16, v17
	v_pk_mul_f32 v[16:17], v[100:101], v[98:99] op_sel_hi:[1,0]
	v_cvt_pk_bf16_f32 v21, v50, v51
	v_pk_fma_f32 v[48:49], v[16:17], v[48:49], v[52:53]
	ds_read_b128 v[16:19], v60 offset:2048
	v_cvt_pk_bf16_f32 v20, v48, v49
	global_store_dwordx2 v[86:87], v[20:21], off
	ds_read_b128 v[20:23], v60 offset:6144
	v_pk_mul_f32 v[46:47], v[94:95], v[98:99] op_sel_hi:[1,0]
	s_waitcnt lgkmcnt(1)
	v_fma_f32 v42, v49, v17, v126
	v_fmac_f32_e32 v42, v48, v16
	v_fmac_f32_e32 v42, v50, v18
	v_fmac_f32_e32 v42, v51, v19
	ds_read_b128 v[16:19], v60 offset:10240
	s_waitcnt lgkmcnt(1)
	v_fma_f32 v41, v49, v21, v127
	v_fmac_f32_e32 v41, v48, v20
	v_fmac_f32_e32 v41, v50, v22
	v_fmac_f32_e32 v41, v51, v23
	ds_read_b128 v[20:23], v60 offset:14336
	s_waitcnt lgkmcnt(1)
	v_fma_f32 v40, v49, v17, v129
	v_fmac_f32_e32 v40, v48, v16
	v_fmac_f32_e32 v40, v50, v18
	v_fmac_f32_e32 v40, v51, v19
	ds_read_b128 v[16:19], v60 offset:18432
	ds_read_b128 v[32:35], v234 offset:3072
	ds_read_b128 v[36:39], v234 offset:7168
	s_waitcnt lgkmcnt(3)
	v_fma_f32 v45, v49, v21, v130
	v_fmac_f32_e32 v45, v48, v20
	v_fmac_f32_e32 v45, v50, v22
	v_fmac_f32_e32 v45, v51, v23
	ds_read_b128 v[20:23], v60 offset:22528
	s_waitcnt lgkmcnt(3)
	v_fma_f32 v44, v49, v17, v132
	v_fmac_f32_e32 v44, v48, v16
	v_fmac_f32_e32 v44, v50, v18
	v_fmac_f32_e32 v44, v51, v19
	ds_read_b128 v[16:19], v60 offset:26624
	s_waitcnt lgkmcnt(1)
	v_fma_f32 v124, v49, v21, v133
	v_fmac_f32_e32 v124, v48, v20
	v_fmac_f32_e32 v124, v50, v22
	v_fmac_f32_e32 v124, v51, v23
	ds_read_b128 v[20:23], v60 offset:30720
	s_waitcnt lgkmcnt(1)
	v_fma_f32 v123, v49, v17, v134
	v_fmac_f32_e32 v123, v48, v16
	v_fmac_f32_e32 v123, v50, v18
	v_fmac_f32_e32 v123, v51, v19
	s_waitcnt lgkmcnt(0)
	v_fma_f32 v122, v49, v21, v135
	v_fmac_f32_e32 v122, v48, v20
	v_fmac_f32_e32 v122, v50, v22
	ds_read_b128 v[16:19], v60 offset:34816
	v_fmac_f32_e32 v122, v51, v23
	ds_read_b128 v[20:23], v60 offset:38912
	s_waitcnt lgkmcnt(1)
	v_fma_f32 v111, v49, v17, v136
	v_fmac_f32_e32 v111, v48, v16
	v_fmac_f32_e32 v111, v50, v18
	s_waitcnt lgkmcnt(0)
	v_fma_f32 v110, v49, v21, v137
	v_fmac_f32_e32 v110, v48, v20
	v_fmac_f32_e32 v111, v51, v19
	v_fmac_f32_e32 v110, v50, v22
	ds_read_b128 v[16:19], v60 offset:43008
	v_fmac_f32_e32 v110, v51, v23
	ds_read_b128 v[20:23], v60 offset:47104
	s_waitcnt lgkmcnt(1)
	v_fma_f32 v109, v49, v17, v138
	v_fmac_f32_e32 v109, v48, v16
	v_fmac_f32_e32 v109, v50, v18
	s_waitcnt lgkmcnt(0)
	v_fma_f32 v108, v49, v21, v131
	v_fmac_f32_e32 v108, v48, v20
	v_fmac_f32_e32 v109, v51, v19
	v_fmac_f32_e32 v108, v50, v22
	ds_read_b128 v[16:19], v60 offset:51200
	v_fmac_f32_e32 v108, v51, v23
	ds_read_b128 v[20:23], v60 offset:55296
	s_waitcnt lgkmcnt(1)
	v_fma_f32 v103, v49, v17, v139
	v_fmac_f32_e32 v103, v48, v16
	v_fmac_f32_e32 v103, v50, v18
	s_waitcnt lgkmcnt(0)
	v_fma_f32 v102, v49, v21, v148
	v_fmac_f32_e32 v102, v48, v20
	v_fmac_f32_e32 v103, v51, v19
	v_fmac_f32_e32 v102, v50, v22
	ds_read_b128 v[16:19], v60 offset:59392
	v_fmac_f32_e32 v102, v51, v23
	ds_read_b128 v[20:23], v60 offset:63488
	s_waitcnt lgkmcnt(1)
	v_fma_f32 v100, v49, v17, v144
	v_fmac_f32_e32 v100, v48, v16
	v_fmac_f32_e32 v100, v50, v18
	s_waitcnt lgkmcnt(0)
	v_fma_f32 v101, v49, v21, v142
	v_fmac_f32_e32 v101, v48, v20
	v_fmac_f32_e32 v101, v50, v22
	v_fmac_f32_e32 v100, v51, v19
	v_fmac_f32_e32 v101, v51, v23
	v_pk_fma_f32 v[52:53], v[46:47], v[32:33], v[36:37]
	v_pk_mul_f32 v[32:33], v[96:97], v[98:99] op_sel_hi:[1,0]
	ds_read_b128 v[94:97], v60 offset:3072
	v_pk_fma_f32 v[54:55], v[32:33], v[34:35], v[38:39]
	v_cvt_pk_bf16_f32 v32, v52, v53
	v_cvt_pk_bf16_f32 v33, v54, v55
	global_store_dwordx2 v[86:87], v[32:33], off offset:512
	ds_read_b128 v[32:35], v60 offset:7168
	s_waitcnt lgkmcnt(1)
	v_mul_f32_e32 v36, v53, v95
	v_fmac_f32_e32 v36, v52, v94
	v_fmac_f32_e32 v36, v54, v96
	v_fmac_f32_e32 v36, v55, v97
	v_add_f32_e32 v94, v42, v36
	ds_read_b128 v[36:39], v60 offset:11264
	ds_read_b128 v[130:133], v60 offset:15360
	s_waitcnt lgkmcnt(2)
	v_fma_f32 v95, v53, v33, v41
	v_fmac_f32_e32 v95, v52, v32
	v_fmac_f32_e32 v95, v54, v34
	s_waitcnt lgkmcnt(1)
	v_fma_f32 v96, v53, v37, v40
	v_fmac_f32_e32 v96, v52, v36
	v_fmac_f32_e32 v96, v54, v38
	v_fmac_f32_e32 v95, v55, v35
	v_fmac_f32_e32 v96, v55, v39
	ds_read_b128 v[40:43], v60 offset:19456
	s_waitcnt lgkmcnt(1)
	v_fma_f32 v97, v53, v131, v45
	v_fmac_f32_e32 v97, v52, v130
	v_fmac_f32_e32 v97, v54, v132
	v_fmac_f32_e32 v97, v55, v133
	ds_read_b128 v[130:133], v60 offset:23552
	s_waitcnt lgkmcnt(1)
	v_fma_f32 v125, v53, v41, v44
	v_fmac_f32_e32 v125, v52, v40
	v_fmac_f32_e32 v125, v54, v42
	v_fmac_f32_e32 v125, v55, v43
	ds_read_b128 v[134:137], v60 offset:27648
	s_waitcnt lgkmcnt(1)
	v_fma_f32 v124, v53, v131, v124
	v_fmac_f32_e32 v124, v52, v130
	v_fmac_f32_e32 v124, v54, v132
	v_fmac_f32_e32 v124, v55, v133
	ds_read_b128 v[130:133], v60 offset:31744
	s_waitcnt lgkmcnt(1)
	v_fma_f32 v98, v53, v135, v123
	v_fmac_f32_e32 v98, v52, v134
	v_fmac_f32_e32 v98, v54, v136
	v_fmac_f32_e32 v98, v55, v137
	ds_read_b128 v[134:137], v60 offset:35840
	s_waitcnt lgkmcnt(1)
	v_fma_f32 v122, v53, v131, v122
	v_fmac_f32_e32 v122, v52, v130
	v_fmac_f32_e32 v122, v54, v132
	v_fmac_f32_e32 v122, v55, v133
	ds_read_b128 v[130:133], v60 offset:39936
	s_waitcnt lgkmcnt(1)
	v_fma_f32 v111, v53, v135, v111
	v_fmac_f32_e32 v111, v52, v134
	v_fmac_f32_e32 v111, v54, v136
	v_fmac_f32_e32 v111, v55, v137
	ds_read_b128 v[134:137], v60 offset:44032
	s_waitcnt lgkmcnt(1)
	v_fma_f32 v110, v53, v131, v110
	v_fmac_f32_e32 v110, v52, v130
	v_fmac_f32_e32 v110, v54, v132
	v_fmac_f32_e32 v110, v55, v133
	ds_read_b128 v[130:133], v60 offset:48128
	s_waitcnt lgkmcnt(1)
	v_fma_f32 v109, v53, v135, v109
	v_fmac_f32_e32 v109, v52, v134
	v_fmac_f32_e32 v109, v54, v136
	v_fmac_f32_e32 v109, v55, v137
	ds_read_b128 v[134:137], v60 offset:52224
	s_waitcnt lgkmcnt(1)
	v_fma_f32 v108, v53, v131, v108
	v_fmac_f32_e32 v108, v52, v130
	v_fmac_f32_e32 v108, v54, v132
	v_fmac_f32_e32 v108, v55, v133
	ds_read_b128 v[130:133], v60 offset:56320
	s_waitcnt lgkmcnt(1)
	v_fma_f32 v103, v53, v135, v103
	v_fmac_f32_e32 v103, v52, v134
	v_fmac_f32_e32 v103, v54, v136
	v_fmac_f32_e32 v103, v55, v137
	ds_read_b128 v[134:137], v60 offset:60416
	s_waitcnt lgkmcnt(1)
	v_fma_f32 v102, v53, v131, v102
	v_fmac_f32_e32 v102, v52, v130
	v_fmac_f32_e32 v102, v54, v132
	v_fmac_f32_e32 v102, v55, v133
	ds_read_b128 v[130:133], v60 offset:64512
	s_waitcnt lgkmcnt(1)
	v_fma_f32 v123, v53, v135, v100
	v_fmac_f32_e32 v123, v52, v134
	v_fmac_f32_e32 v123, v54, v136
	v_fmac_f32_e32 v123, v55, v137
	s_waitcnt lgkmcnt(0)
	v_fma_f32 v129, v53, v131, v101
	v_fmac_f32_e32 v129, v52, v130
	v_fmac_f32_e32 v129, v54, v132
	v_fmac_f32_e32 v129, v55, v133
	v_mov_b32_e32 v100, v48
	v_mov_b32_e32 v101, v52
	v_mov_b32_e32 v52, v49
	v_mov_b32_e32 v48, v218
	v_mov_b32_e32 v126, v214
	v_mov_b32_e32 v130, v222
	v_mov_b32_e32 v127, v230
	v_mov_b32_e32 v49, v238
	v_pk_mul_f32 v[48:49], v[52:53], v[48:49]
	v_mov_b32_e32 v36, v219
	v_pk_fma_f32 v[48:49], v[100:101], v[126:127], v[48:49]
	v_mov_b32_e32 v126, v50
	v_mov_b32_e32 v127, v54
	v_mov_b32_e32 v131, v242
	v_pk_fma_f32 v[48:49], v[126:127], v[130:131], v[48:49]
	v_mov_b32_e32 v54, v51
	v_mov_b32_e32 v50, v226
	v_mov_b32_e32 v51, v246
	v_mov_b32_e32 v32, v215
	v_mov_b32_e32 v37, v239
	v_pk_mul_f32 v[24:25], v[52:53], v[36:37]
	v_pk_fma_f32 v[48:49], v[54:55], v[50:51], v[48:49]
	v_mov_b32_e32 v33, v231
	v_pk_fma_f32 v[24:25], v[100:101], v[32:33], v[24:25]
	v_mov_b32_e32 v40, v223
	v_add_f32_e32 v16, v107, v48
	v_mov_b32_e32 v41, v243
	v_pk_fma_f32 v[20:21], v[126:127], v[40:41], v[24:25]
	v_mov_b32_e32 v44, v227
	v_add_f32_e32 v28, v16, v49
	v_mov_b32_e32 v45, v247
	v_pk_fma_f32 v[16:17], v[54:55], v[44:45], v[20:21]
	v_mov_b32_e32 v20, v220
	v_add_f32_e32 v16, v105, v16
	v_mov_b32_e32 v21, v240
	v_add_f32_e32 v24, v16, v17
	v_mov_b32_e32 v16, v216
	v_mov_b32_e32 v17, v232
	v_pk_mul_f32 v[20:21], v[52:53], v[20:21]
	v_mov_b32_e32 v38, v221
	v_pk_fma_f32 v[16:17], v[100:101], v[16:17], v[20:21]
	v_mov_b32_e32 v20, v224
	v_mov_b32_e32 v21, v244
	v_pk_fma_f32 v[16:17], v[126:127], v[20:21], v[16:17]
	v_mov_b32_e32 v20, v228
	v_mov_b32_e32 v21, v248
	v_pk_fma_f32 v[16:17], v[54:55], v[20:21], v[16:17]
	v_mov_b32_e32 v34, v217
	v_add_f32_e32 v16, v106, v16
	v_add_f32_e32 v20, v16, v17
	v_mov_b32_e32 v39, v241
	v_pk_mul_f32 v[16:17], v[52:53], v[38:39]
	v_mov_b32_e32 v42, v225
	v_mov_b32_e32 v35, v233
	v_pk_fma_f32 v[16:17], v[100:101], v[34:35], v[16:17]
	v_mov_b32_e32 v46, v229
	v_mov_b32_e32 v43, v245
	v_pk_fma_f32 v[16:17], v[126:127], v[42:43], v[16:17]
	v_mov_b32_e32 v47, v249
	v_pk_fma_f32 v[16:17], v[54:55], v[46:47], v[16:17]
	v_add_f32_e32 v16, v104, v16
	v_add_f32_e32 v22, v16, v17
	v_add_f32_dpp v250, v24, v24 row_mirror row_mask:0xf bank_mask:0xf bound_ctrl:1
	v_add_f32_dpp v94, v94, v94 row_mirror row_mask:0xf bank_mask:0xf bound_ctrl:1
	v_add_f32_dpp v125, v125, v125 row_mirror row_mask:0xf bank_mask:0xf bound_ctrl:1
	v_add_f32_dpp v111, v111, v111 row_mirror row_mask:0xf bank_mask:0xf bound_ctrl:1
	v_add_f32_dpp v103, v103, v103 row_mirror row_mask:0xf bank_mask:0xf bound_ctrl:1
	v_add_f32_dpp v250, v20, v20 row_mirror row_mask:0xf bank_mask:0xc bound_ctrl:1
	v_add_f32_dpp v94, v95, v95 row_mirror row_mask:0xf bank_mask:0xc bound_ctrl:1
	v_add_f32_dpp v125, v124, v124 row_mirror row_mask:0xf bank_mask:0xc bound_ctrl:1
	v_add_f32_dpp v111, v110, v110 row_mirror row_mask:0xf bank_mask:0xc bound_ctrl:1
	v_add_f32_dpp v103, v102, v102 row_mirror row_mask:0xf bank_mask:0xc bound_ctrl:1
	v_add_f32_dpp v251, v28, v28 row_mirror row_mask:0xf bank_mask:0xf bound_ctrl:1
	v_add_f32_dpp v96, v96, v96 row_mirror row_mask:0xf bank_mask:0xf bound_ctrl:1
	v_add_f32_dpp v98, v98, v98 row_mirror row_mask:0xf bank_mask:0xf bound_ctrl:1
	v_add_f32_dpp v109, v109, v109 row_mirror row_mask:0xf bank_mask:0xf bound_ctrl:1
	v_add_f32_dpp v123, v123, v123 row_mirror row_mask:0xf bank_mask:0xf bound_ctrl:1
	v_add_f32_dpp v251, v22, v22 row_mirror row_mask:0xf bank_mask:0xc bound_ctrl:1
	v_add_f32_dpp v96, v97, v97 row_mirror row_mask:0xf bank_mask:0xc bound_ctrl:1
	v_add_f32_dpp v98, v122, v122 row_mirror row_mask:0xf bank_mask:0xc bound_ctrl:1
	v_add_f32_dpp v109, v108, v108 row_mirror row_mask:0xf bank_mask:0xc bound_ctrl:1
	v_add_f32_dpp v123, v129, v129 row_mirror row_mask:0xf bank_mask:0xc bound_ctrl:1
	v_add_f32_dpp v250, v250, v250 row_half_mirror row_mask:0xf bank_mask:0xf bound_ctrl:1
	v_add_f32_dpp v94, v94, v94 row_half_mirror row_mask:0xf bank_mask:0xf bound_ctrl:1
	v_add_f32_dpp v125, v125, v125 row_half_mirror row_mask:0xf bank_mask:0xf bound_ctrl:1
	v_add_f32_dpp v111, v111, v111 row_half_mirror row_mask:0xf bank_mask:0xf bound_ctrl:1
	v_add_f32_dpp v103, v103, v103 row_half_mirror row_mask:0xf bank_mask:0xf bound_ctrl:1
	v_add_f32_dpp v250, v251, v251 row_half_mirror row_mask:0xf bank_mask:0xa bound_ctrl:1
	v_add_f32_dpp v94, v96, v96 row_half_mirror row_mask:0xf bank_mask:0xa bound_ctrl:1
	v_add_f32_dpp v125, v98, v98 row_half_mirror row_mask:0xf bank_mask:0xa bound_ctrl:1
	v_add_f32_dpp v111, v109, v109 row_half_mirror row_mask:0xf bank_mask:0xa bound_ctrl:1
	v_add_f32_dpp v103, v123, v123 row_half_mirror row_mask:0xf bank_mask:0xa bound_ctrl:1
	v_add_f32_dpp v250, v250, v250 quad_perm:[1,0,3,2] row_mask:0xf bank_mask:0xf bound_ctrl:1
	v_add_f32_dpp v94, v94, v94 quad_perm:[1,0,3,2] row_mask:0xf bank_mask:0xf bound_ctrl:1
	v_add_f32_dpp v125, v125, v125 quad_perm:[1,0,3,2] row_mask:0xf bank_mask:0xf bound_ctrl:1
	v_add_f32_dpp v111, v111, v111 quad_perm:[1,0,3,2] row_mask:0xf bank_mask:0xf bound_ctrl:1
	v_add_f32_dpp v103, v103, v103 quad_perm:[1,0,3,2] row_mask:0xf bank_mask:0xf bound_ctrl:1
	v_add_f32_dpp v250, v250, v250 quad_perm:[2,3,0,1] row_mask:0xf bank_mask:0xf bound_ctrl:1
	v_add_f32_dpp v94, v94, v94 quad_perm:[2,3,0,1] row_mask:0xf bank_mask:0xf bound_ctrl:1
	v_add_f32_dpp v125, v125, v125 quad_perm:[2,3,0,1] row_mask:0xf bank_mask:0xf bound_ctrl:1
	v_add_f32_dpp v111, v111, v111 quad_perm:[2,3,0,1] row_mask:0xf bank_mask:0xf bound_ctrl:1
	v_add_f32_dpp v103, v103, v103 quad_perm:[2,3,0,1] row_mask:0xf bank_mask:0xf bound_ctrl:1
	v_readlane_b32 s2, v250, 20
	v_readlane_b32 s4, v250, 52
	v_readlane_b32 s0, v250, 4
	v_readlane_b32 s1, v250, 36
	v_mov_b32_e32 v16, s2
	v_mov_b32_e32 v17, s4
	v_readlane_b32 s2, v250, 16
	v_readlane_b32 s4, v250, 48
	v_pk_add_f32 v[16:17], s[0:1], v[16:17]
	v_readlane_b32 s0, v250, 0
	v_readlane_b32 s1, v250, 32
	v_mov_b32_e32 v18, s2
	v_mov_b32_e32 v19, s4
	v_readlane_b32 s2, v250, 24
	v_readlane_b32 s4, v250, 56
	v_pk_add_f32 v[18:19], s[0:1], v[18:19]
	v_readlane_b32 s0, v250, 8
	v_readlane_b32 s1, v250, 40
	v_mov_b32_e32 v20, s2
	v_mov_b32_e32 v21, s4
	v_pk_add_f32 v[20:21], s[0:1], v[20:21]
	v_mov_b32_e32 v25, v18
	v_add_f32_e32 v26, v20, v21
	v_mov_b32_e32 v18, v17
	v_readlane_b32 s2, v250, 28
	v_readlane_b32 s4, v250, 60
	v_readlane_b32 s0, v250, 12
	v_readlane_b32 s1, v250, 44
	v_mov_b32_e32 v20, s2
	v_mov_b32_e32 v21, s4
	v_pk_add_f32 v[20:21], s[0:1], v[20:21]
	v_add_f32_e32 v27, v20, v21
	v_readlane_b32 s20, v94, 0
	v_readlane_b32 s4, v94, 16
	v_readlane_b32 s21, v94, 32
	v_readlane_b32 s5, v94, 48
	v_readlane_b32 s91, v94, 8
	v_readlane_b32 s95, v94, 24
	v_readlane_b32 s94, v94, 40
	v_readlane_b32 s92, v94, 56
	v_readlane_b32 s6, v94, 4
	v_readlane_b32 s75, v94, 20
	v_readlane_b32 s74, v94, 36
	v_readlane_b32 s84, v94, 52
	v_readlane_b32 s97, v94, 12
	v_readlane_b32 s9, v94, 28
	v_readlane_b32 s8, v94, 44
	v_readlane_b32 s12, v94, 60
	v_readlane_b32 s59, v125, 0
	v_readlane_b32 s61, v125, 16
	v_readlane_b32 s60, v125, 32
	v_readlane_b32 s82, v125, 48
	v_readlane_b32 s52, v125, 8
	v_readlane_b32 s54, v125, 24
	v_readlane_b32 s53, v125, 40
	v_readlane_b32 s93, v125, 56
	v_readlane_b32 s85, v125, 4
	v_readlane_b32 s87, v125, 20
	v_readlane_b32 s86, v125, 36
	v_readlane_b32 s90, v125, 52
	v_readlane_b32 s13, v125, 12
	v_readlane_b32 s24, v125, 28
	v_readlane_b32 s16, v125, 44
	v_readlane_b32 s17, v125, 60
	v_readlane_b32 s83, v111, 0
	v_readlane_b32 s89, v111, 16
	v_readlane_b32 s88, v111, 32
	v_readlane_b32 s96, v111, 48
	v_readlane_b32 s55, v111, 8
	v_readlane_b32 s57, v111, 24
	v_readlane_b32 s56, v111, 40
	v_readlane_b32 s58, v111, 56
	v_readlane_b32 s46, v111, 4
	v_readlane_b32 s48, v111, 20
	v_readlane_b32 s47, v111, 36
	v_readlane_b32 s49, v111, 52
	v_readlane_b32 s38, v111, 12
	v_readlane_b32 s40, v111, 28
	v_readlane_b32 s39, v111, 44
	v_readlane_b32 s41, v111, 60
	v_readlane_b32 s34, v103, 0
	v_readlane_b32 s36, v103, 16
	v_readlane_b32 s35, v103, 32
	v_readlane_b32 s37, v103, 48
	v_readlane_b32 s29, v103, 8
	v_readlane_b32 s31, v103, 24
	v_readlane_b32 s30, v103, 40
	v_readlane_b32 s33, v103, 56
	v_readlane_b32 s25, v103, 4
	v_readlane_b32 s28, v103, 20
	v_readlane_b32 s50, v103, 36
	v_readlane_b32 s51, v103, 52
	v_mov_b32_e32 v24, v16
	v_pk_add_f32 v[16:17], v[24:25], v[18:19]
	v_mov_b32_e32 v20, v178
	v_mov_b32_e32 v21, v179
	v_mov_b32_e32 v22, v180
	v_mov_b32_e32 v23, v181
	v_add_f32_e32 v19, v26, v22
	v_pk_add_f32 v[16:17], v[16:17], v[20:21]
	v_add_f32_e32 v18, v27, v23
	v_cmp_gt_f32_e32 vcc, v17, v16
	v_mov_b32_e32 v22, 0
	v_readlane_b32 s42, v103, 12
	v_cndmask_b32_e32 v20, v16, v17, vcc
	v_cmp_gt_f32_e64 s[18:19], v19, v20
	v_cndmask_b32_e64 v21, 0, 1, vcc
	s_and_b64 s[14:15], s[18:19], exec
	v_cndmask_b32_e64 v20, v20, v19, s[18:19]
	v_cmp_ngt_f32_e64 s[0:1], v18, v20
	v_readfirstlane_b32 s2, v21
	s_cselect_b32 s2, 2, s2
	s_and_b64 s[14:15], s[0:1], exec
	s_cselect_b32 s2, s2, 3
	s_cmp_eq_u32 s2, 0
	s_cselect_b64 s[26:27], -1, 0
	s_cmp_lg_u32 s2, 0
	v_mov_b32_e32 v21, 0
	v_readlane_b32 s44, v103, 28
	v_readlane_b32 s43, v103, 44
	v_readlane_b32 s45, v103, 60
	v_cmp_gt_f32_e64 s[14:15], v18, v20
	s_waitcnt lgkmcnt(0)
	s_cbranch_scc0 .LBB0_560
	v_cndmask_b32_e64 v23, 0, 1, s[26:27]
	v_cmp_ne_u32_e64 s[20:21], 1, v23
	s_andn2_b64 vcc, exec, s[26:27]
	s_cbranch_vccz .LBB0_561

.LBB0_1676:
	s_add_i32 s21, s19, 1
	s_waitcnt vmcnt(0)
	v_mov_b64_e32 v[38:39], v[84:85]
	v_mov_b64_e32 v[32:33], v[92:93]
	v_mov_b64_e32 v[34:35], v[90:91]
	v_mov_b64_e32 v[36:37], v[88:89]
	v_mov_b32_e32 v0, s21
	v_min_u32_e32 v0, 15, v0
	v_mov_b32_e32 v1, 0
	v_lshl_add_u64 v[0:1], v[82:83], 0, v[0:1]
	v_lshlrev_b64 v[2:3], 12, v[0:1]
	v_lshlrev_b64 v[0:1], 11, v[0:1]
	v_lshl_add_u64 v[12:13], v[62:63], 0, v[2:3]
	v_lshl_add_u64 v[92:93], v[64:65], 0, v[0:1]
	global_load_dwordx4 v[0:3], v[12:13], off
	global_load_dwordx2 v[84:85], v[92:93], off
	global_load_dwordx4 v[4:7], v[12:13], off offset:1024
	global_load_dwordx2 v[88:89], v[92:93], off offset:512
	global_load_dwordx4 v[8:11], v[12:13], off offset:2048
	global_load_dwordx2 v[90:91], v[92:93], off offset:1024
	s_nop 0
	global_load_dwordx4 v[12:15], v[12:13], off offset:3072
	s_nop 0
	global_load_dwordx2 v[92:93], v[92:93], off offset:1536
	v_lshlrev_b32_e32 v40, 16, v38
	v_and_b32_e32 v41, 0xffff0000, v38
	v_lshlrev_b32_e32 v38, 16, v39
	v_and_b32_e32 v39, 0xffff0000, v39
	v_lshlrev_b32_e32 v54, 16, v36
	v_and_b32_e32 v55, 0xffff0000, v36
	v_lshlrev_b32_e32 v94, 16, v37
	v_and_b32_e32 v95, 0xffff0000, v37
	v_lshlrev_b32_e32 v96, 16, v34
	v_and_b32_e32 v97, 0xffff0000, v34
	v_lshlrev_b32_e32 v100, 16, v35
	v_and_b32_e32 v101, 0xffff0000, v35
	v_lshlrev_b32_e32 v102, 16, v32
	v_and_b32_e32 v103, 0xffff0000, v32
	v_lshlrev_b32_e32 v104, 16, v33
	v_and_b32_e32 v105, 0xffff0000, v33
	v_pk_fma_f32 v[106:107], v[30:31], s[20:21], v[38:39] op_sel_hi:[1,0,1]
	ds_read_b128 v[30:33], v234
	ds_read_b128 v[34:37], v234 offset:4096
	v_pk_fma_f32 v[28:29], v[28:29], s[20:21], v[40:41] op_sel_hi:[1,0,1]
	v_pk_fma_f32 v[20:21], v[20:21], s[20:21], v[54:55] op_sel_hi:[1,0,1]
	v_add_f32_e32 v38, v28, v29
	v_add_f32_e32 v38, v38, v106
	v_pk_fma_f32 v[22:23], v[22:23], s[20:21], v[94:95] op_sel_hi:[1,0,1]
	v_add_f32_e32 v54, v20, v21
	v_pk_fma_f32 v[24:25], v[24:25], s[20:21], v[96:97] op_sel_hi:[1,0,1]
	v_add_f32_e32 v38, v107, v38
	v_add_f32_e32 v54, v54, v22
	v_pk_fma_f32 v[26:27], v[26:27], s[20:21], v[100:101] op_sel_hi:[1,0,1]
	v_add_f32_e32 v55, v24, v25
	v_add_f32_e32 v98, 0, v38
	v_add_f32_e32 v54, v23, v54
	v_add_f32_e32 v55, v55, v26
	v_add_f32_e32 v54, v98, v54
	v_add_f32_e32 v55, v27, v55
	v_pk_fma_f32 v[16:17], v[16:17], s[20:21], v[102:103] op_sel_hi:[1,0,1]
	v_add_f32_e32 v54, v54, v55
	v_pk_fma_f32 v[18:19], v[18:19], s[20:21], v[104:105] op_sel_hi:[1,0,1]
	v_add_f32_e32 v55, v16, v17
	v_add_f32_e32 v55, v55, v18
	v_add_f32_e32 v55, v19, v55
	v_add_f32_e32 v54, v54, v55
	ds_read_b128 v[38:41], v60
	ds_read_b128 v[42:45], v60 offset:4096
	ds_read_b128 v[46:49], v60 offset:8192
	ds_read_b128 v[50:53], v60 offset:12288
	ds_read_b128 v[108:111], v60 offset:16384
	ds_read_b128 v[122:125], v60 offset:20480
	ds_read_b128 v[130:133], v60 offset:24576
	ds_read_b128 v[134:137], v60 offset:28672
	ds_read_b128 v[138:141], v60 offset:32768
	ds_read_b128 v[142:145], v60 offset:36864
	ds_read_b128 v[146:149], v60 offset:40960
	ds_read_b128 v[150:153], v60 offset:45056
	ds_read_b128 v[154:157], v60 offset:49152
	v_add_f32_dpp v54, v54, v54 quad_perm:[1,0,3,2] row_mask:0xf bank_mask:0xf bound_ctrl:1
	s_nop 1
	v_add_f32_dpp v54, v54, v54 quad_perm:[2,3,0,1] row_mask:0xf bank_mask:0xf bound_ctrl:1
	s_nop 1
	v_add_f32_dpp v54, v54, v54 row_half_mirror row_mask:0xf bank_mask:0xf bound_ctrl:1
	s_nop 1
	v_add_f32_dpp v54, v54, v54 row_mirror row_mask:0xf bank_mask:0xf bound_ctrl:1
	s_nop 0
	v_readlane_b32 s2, v54, 16
	v_readlane_b32 s10, v54, 48
	v_readlane_b32 s0, v54, 0
	v_readlane_b32 s1, v54, 32
	v_mov_b32_e32 v54, s2
	v_mov_b32_e32 v55, s10
	v_pk_add_f32 v[54:55], s[0:1], v[54:55]
	s_nop 0
	v_add_f32_e32 v54, v54, v55
	v_mul_f32_e32 v54, 0x3a800000, v54
	v_pk_add_f32 v[28:29], v[28:29], v[54:55] op_sel_hi:[1,0] neg_lo:[0,1] neg_hi:[0,1]
	v_pk_add_f32 v[126:127], v[106:107], v[54:55] op_sel_hi:[1,0] neg_lo:[0,1] neg_hi:[0,1]
	v_pk_mul_f32 v[104:105], v[28:29], v[28:29]
	v_pk_mul_f32 v[106:107], v[126:127], v[126:127]
	v_pk_add_f32 v[158:159], v[20:21], v[54:55] op_sel_hi:[1,0] neg_lo:[0,1] neg_hi:[0,1]
	v_pk_add_f32 v[160:161], v[22:23], v[54:55] op_sel_hi:[1,0] neg_lo:[0,1] neg_hi:[0,1]
	v_pk_add_f32 v[100:101], v[24:25], v[54:55] op_sel_hi:[1,0] neg_lo:[0,1] neg_hi:[0,1]
	v_pk_add_f32 v[102:103], v[26:27], v[54:55] op_sel_hi:[1,0] neg_lo:[0,1] neg_hi:[0,1]
	v_pk_add_f32 v[94:95], v[16:17], v[54:55] op_sel_hi:[1,0] neg_lo:[0,1] neg_hi:[0,1]
	v_pk_add_f32 v[96:97], v[18:19], v[54:55] op_sel_hi:[1,0] neg_lo:[0,1] neg_hi:[0,1]
	v_add_f32_e32 v54, v104, v105
	v_add_f32_e32 v54, v106, v54
	v_pk_mul_f32 v[20:21], v[158:159], v[158:159]
	v_add_f32_e32 v54, v107, v54
	v_add_f32_e32 v20, v20, v54
	v_pk_mul_f32 v[22:23], v[160:161], v[160:161]
	v_add_f32_e32 v20, v21, v20
	v_add_f32_e32 v20, v22, v20
	v_pk_mul_f32 v[24:25], v[100:101], v[100:101]
	v_add_f32_e32 v20, v23, v20
	v_add_f32_e32 v20, v24, v20
	v_pk_mul_f32 v[26:27], v[102:103], v[102:103]
	v_add_f32_e32 v20, v25, v20
	v_add_f32_e32 v20, v26, v20
	v_pk_mul_f32 v[16:17], v[94:95], v[94:95]
	v_add_f32_e32 v20, v27, v20
	v_add_f32_e32 v16, v16, v20
	v_pk_mul_f32 v[18:19], v[96:97], v[96:97]
	v_add_f32_e32 v16, v17, v16
	v_add_f32_e32 v16, v18, v16
	v_add_f32_e32 v16, v19, v16
	s_nop 1
	v_add_f32_dpp v16, v16, v16 quad_perm:[1,0,3,2] row_mask:0xf bank_mask:0xf bound_ctrl:1
	s_nop 1
	v_add_f32_dpp v16, v16, v16 quad_perm:[2,3,0,1] row_mask:0xf bank_mask:0xf bound_ctrl:1
	s_nop 1
	v_add_f32_dpp v16, v16, v16 row_half_mirror row_mask:0xf bank_mask:0xf bound_ctrl:1
	s_nop 1
	v_add_f32_dpp v16, v16, v16 row_mirror row_mask:0xf bank_mask:0xf bound_ctrl:1
	s_nop 0
	v_readlane_b32 s2, v16, 16
	v_readlane_b32 s10, v16, 48
	v_readlane_b32 s0, v16, 0
	v_readlane_b32 s1, v16, 32
	v_mov_b32_e32 v16, s2
	v_mov_b32_e32 v17, s10
	v_pk_add_f32 v[16:17], s[0:1], v[16:17]
	s_mov_b32 s0, 0x800000
	v_add_f32_e32 v16, v16, v17
	v_fmamk_f32 v16, v16, 0x3a800000, v116
	v_cmp_gt_f32_e32 vcc, s0, v16
	v_mul_f32_e32 v17, 0x4b800000, v16
	s_nop 0
	v_cndmask_b32_e32 v16, v16, v17, vcc
	v_rsq_f32_e32 v54, v16
	ds_read_b128 v[16:19], v60 offset:53248
	s_waitcnt lgkmcnt(15)
	ds_read_b128 v[20:23], v60 offset:57344
	s_waitcnt lgkmcnt(15)
	ds_read_b128 v[24:27], v60 offset:61440
	s_waitcnt lgkmcnt(15)
	v_mul_f32_e32 v55, 0x45800000, v54
	v_cndmask_b32_e32 v98, v54, v55, vcc
	v_pk_mul_f32 v[28:29], v[28:29], v[98:99] op_sel_hi:[1,0]
	v_pk_fma_f32 v[106:107], v[30:31], v[28:29], v[34:35]
	v_pk_mul_f32 v[28:29], v[126:127], v[98:99] op_sel_hi:[1,0]
	s_waitcnt lgkmcnt(2)
	v_mul_f32_e32 v17, v107, v17
	v_pk_fma_f32 v[104:105], v[32:33], v[28:29], v[36:37]
	v_cvt_pk_bf16_f32 v28, v106, v107
	v_cvt_pk_bf16_f32 v29, v104, v105
	global_store_dwordx2 v[86:87], v[28:29], off offset:-1024
	v_mul_f32_e32 v54, v39, v107
	v_fmac_f32_e32 v54, v38, v106
	ds_read_b128 v[32:35], v234 offset:1024
	ds_read_b128 v[36:39], v234 offset:5120
	v_fmac_f32_e32 v54, v104, v40
	v_fmac_f32_e32 v54, v105, v41
	v_mul_f32_e32 v55, v107, v43
	v_fmac_f32_e32 v55, v106, v42
	v_fmac_f32_e32 v55, v104, v44
	v_fmac_f32_e32 v55, v105, v45
	v_mul_f32_e32 v28, v107, v47
	v_fmac_f32_e32 v28, v106, v46
	v_fmac_f32_e32 v28, v104, v48
	v_fmac_f32_e32 v28, v105, v49
	v_add_f32_e32 v46, 0, v28
	v_mul_f32_e32 v45, v107, v51
	v_fmac_f32_e32 v45, v106, v50
	v_fmac_f32_e32 v45, v104, v52
	v_fmac_f32_e32 v45, v105, v53
	v_mul_f32_e32 v44, v107, v109
	v_fmac_f32_e32 v44, v106, v108
	v_fmac_f32_e32 v44, v104, v110
	v_fmac_f32_e32 v44, v105, v111
	v_mul_f32_e32 v53, v107, v123
	v_fmac_f32_e32 v53, v106, v122
	v_fmac_f32_e32 v53, v104, v124
	v_fmac_f32_e32 v53, v105, v125
	v_mul_f32_e32 v52, v107, v131
	v_fmac_f32_e32 v52, v106, v130
	v_fmac_f32_e32 v52, v104, v132
	v_fmac_f32_e32 v52, v105, v133
	v_mul_f32_e32 v51, v107, v135
	v_fmac_f32_e32 v51, v106, v134
	v_fmac_f32_e32 v51, v104, v136
	v_fmac_f32_e32 v51, v105, v137
	v_mul_f32_e32 v50, v107, v139
	v_fmac_f32_e32 v50, v106, v138
	v_fmac_f32_e32 v50, v104, v140
	v_fmac_f32_e32 v50, v105, v141
	v_mul_f32_e32 v49, v107, v143
	v_fmac_f32_e32 v49, v106, v142
	v_fmac_f32_e32 v49, v104, v144
	v_fmac_f32_e32 v49, v105, v145
	v_mul_f32_e32 v48, v107, v147
	v_fmac_f32_e32 v48, v106, v146
	v_fmac_f32_e32 v48, v104, v148
	v_fmac_f32_e32 v48, v105, v149
	v_mul_f32_e32 v131, v107, v151
	v_fmac_f32_e32 v17, v106, v16
	s_waitcnt lgkmcnt(3)
	v_mul_f32_e32 v122, v107, v21
	v_fmac_f32_e32 v131, v106, v150
	v_fmac_f32_e32 v122, v106, v20
	v_fmac_f32_e32 v131, v104, v152
	v_fmac_f32_e32 v122, v104, v22
	v_fmac_f32_e32 v131, v105, v153
	v_fmac_f32_e32 v122, v105, v23
	v_mul_f32_e32 v125, v107, v155
	s_waitcnt lgkmcnt(2)
	v_mul_f32_e32 v123, v107, v25
	v_fmac_f32_e32 v125, v106, v154
	v_fmac_f32_e32 v123, v106, v24
	v_fmac_f32_e32 v125, v104, v156
	v_fmac_f32_e32 v17, v104, v18
	v_fmac_f32_e32 v123, v104, v26
	v_fmac_f32_e32 v125, v105, v157
	v_fmac_f32_e32 v17, v105, v19
	v_fmac_f32_e32 v123, v105, v27
	v_pk_mul_f32 v[40:41], v[158:159], v[98:99] op_sel_hi:[1,0]
	v_add_f32_e32 v124, 0, v17
	s_waitcnt lgkmcnt(0)
	v_pk_fma_f32 v[108:109], v[40:41], v[32:33], v[36:37]
	ds_read_b128 v[40:43], v60 offset:1024
	ds_read_b128 v[134:137], v60 offset:21504
	v_pk_mul_f32 v[32:33], v[160:161], v[98:99] op_sel_hi:[1,0]
	ds_read_b128 v[142:145], v60 offset:29696
	v_pk_fma_f32 v[110:111], v[32:33], v[34:35], v[38:39]
	s_waitcnt lgkmcnt(2)
	v_fma_f32 v126, v109, v41, v54
	v_cvt_pk_bf16_f32 v32, v108, v109
	v_cvt_pk_bf16_f32 v33, v110, v111
	v_fmac_f32_e32 v126, v108, v40
	global_store_dwordx2 v[86:87], v[32:33], off offset:-512
	ds_read_b128 v[32:35], v60 offset:5120
	v_fmac_f32_e32 v126, v110, v42
	v_fmac_f32_e32 v126, v111, v43
	s_waitcnt lgkmcnt(2)
	v_fma_f32 v133, v109, v135, v53
	s_waitcnt lgkmcnt(1)
	v_fma_f32 v135, v109, v143, v51
	v_fmac_f32_e32 v135, v108, v142
	v_fmac_f32_e32 v135, v110, v144
	v_fmac_f32_e32 v135, v111, v145
	ds_read_b128 v[144:147], v60 offset:50176
	s_waitcnt lgkmcnt(1)
	v_fma_f32 v127, v109, v33, v55
	v_fmac_f32_e32 v127, v108, v32
	v_fmac_f32_e32 v127, v110, v34
	v_fmac_f32_e32 v127, v111, v35
	ds_read_b128 v[36:39], v60 offset:9216
	ds_read_b128 v[32:35], v60 offset:13312
	ds_read_b128 v[40:43], v60 offset:17408
	ds_read_b128 v[138:141], v60 offset:25600
	v_fmac_f32_e32 v133, v108, v134
	v_fmac_f32_e32 v133, v110, v136
	s_waitcnt lgkmcnt(3)
	v_fma_f32 v129, v109, v37, v46
	s_waitcnt lgkmcnt(2)
	v_fma_f32 v130, v109, v33, v45
	v_fmac_f32_e32 v133, v111, v137
	v_fmac_f32_e32 v129, v108, v36
	v_fmac_f32_e32 v130, v108, v32
	s_waitcnt lgkmcnt(0)
	v_fma_f32 v134, v109, v139, v52
	v_fmac_f32_e32 v129, v110, v38
	v_fmac_f32_e32 v130, v110, v34
	v_fma_f32 v132, v109, v41, v44
	v_fmac_f32_e32 v134, v108, v138
	v_fmac_f32_e32 v129, v111, v39
	v_fmac_f32_e32 v130, v111, v35
	v_fmac_f32_e32 v132, v108, v40
	v_fmac_f32_e32 v134, v110, v140
	v_fmac_f32_e32 v132, v110, v42
	v_fmac_f32_e32 v134, v111, v141
	v_fmac_f32_e32 v132, v111, v43
	ds_read_b128 v[52:55], v60 offset:33792
	ds_read_b128 v[138:141], v60 offset:37888
	s_waitcnt lgkmcnt(1)
	v_fma_f32 v136, v109, v53, v50
	v_fmac_f32_e32 v136, v108, v52
	v_fmac_f32_e32 v136, v110, v54
	v_fmac_f32_e32 v136, v111, v55
	ds_read_b128 v[50:53], v60 offset:41984
	s_waitcnt lgkmcnt(1)
	v_fma_f32 v137, v109, v139, v49
	v_fmac_f32_e32 v137, v108, v138
	v_fmac_f32_e32 v137, v110, v140
	v_fmac_f32_e32 v137, v111, v141
	ds_read_b128 v[140:143], v60 offset:46080
	s_waitcnt lgkmcnt(1)
	v_fma_f32 v138, v109, v51, v48
	v_fmac_f32_e32 v138, v108, v50
	v_fmac_f32_e32 v138, v110, v52
	v_fmac_f32_e32 v138, v111, v53
	ds_read_b128 v[48:51], v234 offset:2048
	ds_read_b128 v[52:55], v234 offset:6144
	s_waitcnt lgkmcnt(2)
	v_fma_f32 v131, v109, v141, v131
	v_fmac_f32_e32 v131, v108, v140
	v_fmac_f32_e32 v131, v110, v142
	v_fmac_f32_e32 v131, v111, v143
	ds_read_b128 v[140:143], v60 offset:54272
	v_fma_f32 v139, v109, v145, v125
	v_fmac_f32_e32 v139, v108, v144
	v_fmac_f32_e32 v139, v110, v146
	v_fmac_f32_e32 v139, v111, v147
	ds_read_b128 v[144:147], v60 offset:58368
	s_waitcnt lgkmcnt(1)
	v_fma_f32 v148, v109, v141, v124
	v_fmac_f32_e32 v148, v108, v140
	v_fmac_f32_e32 v148, v110, v142
	v_fmac_f32_e32 v148, v111, v143
	ds_read_b128 v[140:143], v60 offset:62464
	s_waitcnt lgkmcnt(1)
	v_mul_f32_e32 v124, v109, v145
	v_fmac_f32_e32 v124, v108, v144
	v_fmac_f32_e32 v124, v110, v146
	v_fmac_f32_e32 v124, v111, v147
	v_add_f32_e32 v144, v122, v124
	s_waitcnt lgkmcnt(0)
	v_mul_f32_e32 v122, v109, v141
	v_fmac_f32_e32 v122, v108, v140
	v_fmac_f32_e32 v122, v110, v142
	v_fmac_f32_e32 v122, v111, v143
	v_add_f32_e32 v142, v123, v122
	v_mov_b32_e32 v122, v106
	v_mov_b32_e32 v123, v108
	v_mov_b32_e32 v108, v107
	v_mov_b32_e32 v106, v186
	v_mov_b32_e32 v124, v182
	v_mov_b32_e32 v140, v190
	v_mov_b32_e32 v125, v198
	v_mov_b32_e32 v107, v202
	v_pk_mul_f32 v[106:107], v[108:109], v[106:107]
	v_mov_b32_e32 v36, v187
	v_pk_fma_f32 v[106:107], v[122:123], v[124:125], v[106:107]
	v_mov_b32_e32 v124, v104
	v_mov_b32_e32 v125, v110
	v_mov_b32_e32 v110, v105
	v_mov_b32_e32 v104, v194
	v_mov_b32_e32 v141, v206
	v_pk_fma_f32 v[106:107], v[124:125], v[140:141], v[106:107]
	v_mov_b32_e32 v105, v210
	v_mov_b32_e32 v32, v183
	v_mov_b32_e32 v37, v203
	v_pk_mul_f32 v[24:25], v[108:109], v[36:37]
	v_pk_fma_f32 v[104:105], v[110:111], v[104:105], v[106:107]
	v_mov_b32_e32 v33, v199
	v_pk_fma_f32 v[24:25], v[122:123], v[32:33], v[24:25]
	v_mov_b32_e32 v40, v191
	v_add_f32_e32 v16, 0, v104
	v_mov_b32_e32 v41, v207
	v_pk_fma_f32 v[20:21], v[124:125], v[40:41], v[24:25]
	v_mov_b32_e32 v44, v195
	v_add_f32_e32 v107, v16, v105
	v_mov_b32_e32 v45, v211
	v_pk_fma_f32 v[16:17], v[110:111], v[44:45], v[20:21]
	v_mov_b32_e32 v20, v188
	v_add_f32_e32 v16, 0, v16
	v_mov_b32_e32 v21, v204
	v_add_f32_e32 v105, v16, v17
	v_mov_b32_e32 v16, v184
	v_mov_b32_e32 v17, v200
	v_pk_mul_f32 v[20:21], v[108:109], v[20:21]
	v_mov_b32_e32 v38, v189
	v_pk_fma_f32 v[16:17], v[122:123], v[16:17], v[20:21]
	v_mov_b32_e32 v20, v192
	v_mov_b32_e32 v21, v208
	v_pk_fma_f32 v[16:17], v[124:125], v[20:21], v[16:17]
	v_mov_b32_e32 v20, v196
	v_mov_b32_e32 v21, v212
	v_pk_fma_f32 v[16:17], v[110:111], v[20:21], v[16:17]
	v_mov_b32_e32 v34, v185
	v_add_f32_e32 v16, 0, v16
	v_add_f32_e32 v106, v16, v17
	v_mov_b32_e32 v39, v205
	v_pk_mul_f32 v[16:17], v[108:109], v[38:39]
	v_mov_b32_e32 v42, v193
	v_mov_b32_e32 v35, v201
	v_pk_fma_f32 v[16:17], v[122:123], v[34:35], v[16:17]
	v_mov_b32_e32 v46, v197
	v_mov_b32_e32 v43, v209
	v_pk_fma_f32 v[16:17], v[124:125], v[42:43], v[16:17]
	v_pk_mul_f32 v[20:21], v[102:103], v[98:99] op_sel_hi:[1,0]
	v_mov_b32_e32 v47, v213
	v_pk_fma_f32 v[16:17], v[110:111], v[46:47], v[16:17]
	v_pk_fma_f32 v[50:51], v[20:21], v[50:51], v[54:55]
	v_add_f32_e32 v16, 0, v16
	v_add_f32_e32 v104, v16, v17
	v_pk_mul_f32 v[16:17], v[100:101], v[98:99] op_sel_hi:[1,0]
	v_cvt_pk_bf16_f32 v21, v50, v51
	v_pk_fma_f32 v[48:49], v[16:17], v[48:49], v[52:53]
	ds_read_b128 v[16:19], v60 offset:2048
	v_cvt_pk_bf16_f32 v20, v48, v49
	global_store_dwordx2 v[86:87], v[20:21], off
	ds_read_b128 v[20:23], v60 offset:6144
	v_pk_mul_f32 v[46:47], v[94:95], v[98:99] op_sel_hi:[1,0]
	s_waitcnt lgkmcnt(1)
	v_fma_f32 v42, v49, v17, v126
	v_fmac_f32_e32 v42, v48, v16
	v_fmac_f32_e32 v42, v50, v18
	v_fmac_f32_e32 v42, v51, v19
	ds_read_b128 v[16:19], v60 offset:10240
	s_waitcnt lgkmcnt(1)
	v_fma_f32 v41, v49, v21, v127
	v_fmac_f32_e32 v41, v48, v20
	v_fmac_f32_e32 v41, v50, v22
	v_fmac_f32_e32 v41, v51, v23
	ds_read_b128 v[20:23], v60 offset:14336
	s_waitcnt lgkmcnt(1)
	v_fma_f32 v40, v49, v17, v129
	v_fmac_f32_e32 v40, v48, v16
	v_fmac_f32_e32 v40, v50, v18
	v_fmac_f32_e32 v40, v51, v19
	ds_read_b128 v[16:19], v60 offset:18432
	ds_read_b128 v[32:35], v234 offset:3072
	ds_read_b128 v[36:39], v234 offset:7168
	s_waitcnt lgkmcnt(3)
	v_fma_f32 v45, v49, v21, v130
	v_fmac_f32_e32 v45, v48, v20
	v_fmac_f32_e32 v45, v50, v22
	v_fmac_f32_e32 v45, v51, v23
	ds_read_b128 v[20:23], v60 offset:22528
	s_waitcnt lgkmcnt(3)
	v_fma_f32 v44, v49, v17, v132
	v_fmac_f32_e32 v44, v48, v16
	v_fmac_f32_e32 v44, v50, v18
	v_fmac_f32_e32 v44, v51, v19
	ds_read_b128 v[16:19], v60 offset:26624
	s_waitcnt lgkmcnt(1)
	v_fma_f32 v124, v49, v21, v133
	v_fmac_f32_e32 v124, v48, v20
	v_fmac_f32_e32 v124, v50, v22
	v_fmac_f32_e32 v124, v51, v23
	ds_read_b128 v[20:23], v60 offset:30720
	s_waitcnt lgkmcnt(1)
	v_fma_f32 v123, v49, v17, v134
	v_fmac_f32_e32 v123, v48, v16
	v_fmac_f32_e32 v123, v50, v18
	v_fmac_f32_e32 v123, v51, v19
	s_waitcnt lgkmcnt(0)
	v_fma_f32 v122, v49, v21, v135
	v_fmac_f32_e32 v122, v48, v20
	v_fmac_f32_e32 v122, v50, v22
	ds_read_b128 v[16:19], v60 offset:34816
	v_fmac_f32_e32 v122, v51, v23
	ds_read_b128 v[20:23], v60 offset:38912
	s_waitcnt lgkmcnt(1)
	v_fma_f32 v111, v49, v17, v136
	v_fmac_f32_e32 v111, v48, v16
	v_fmac_f32_e32 v111, v50, v18
	s_waitcnt lgkmcnt(0)
	v_fma_f32 v110, v49, v21, v137
	v_fmac_f32_e32 v110, v48, v20
	v_fmac_f32_e32 v111, v51, v19
	v_fmac_f32_e32 v110, v50, v22
	ds_read_b128 v[16:19], v60 offset:43008
	v_fmac_f32_e32 v110, v51, v23
	ds_read_b128 v[20:23], v60 offset:47104
	s_waitcnt lgkmcnt(1)
	v_fma_f32 v109, v49, v17, v138
	v_fmac_f32_e32 v109, v48, v16
	v_fmac_f32_e32 v109, v50, v18
	s_waitcnt lgkmcnt(0)
	v_fma_f32 v108, v49, v21, v131
	v_fmac_f32_e32 v108, v48, v20
	v_fmac_f32_e32 v109, v51, v19
	v_fmac_f32_e32 v108, v50, v22
	ds_read_b128 v[16:19], v60 offset:51200
	v_fmac_f32_e32 v108, v51, v23
	ds_read_b128 v[20:23], v60 offset:55296
	s_waitcnt lgkmcnt(1)
	v_fma_f32 v103, v49, v17, v139
	v_fmac_f32_e32 v103, v48, v16
	v_fmac_f32_e32 v103, v50, v18
	s_waitcnt lgkmcnt(0)
	v_fma_f32 v102, v49, v21, v148
	v_fmac_f32_e32 v102, v48, v20
	v_fmac_f32_e32 v103, v51, v19
	v_fmac_f32_e32 v102, v50, v22
	ds_read_b128 v[16:19], v60 offset:59392
	v_fmac_f32_e32 v102, v51, v23
	ds_read_b128 v[20:23], v60 offset:63488
	s_waitcnt lgkmcnt(1)
	v_fma_f32 v100, v49, v17, v144
	v_fmac_f32_e32 v100, v48, v16
	v_fmac_f32_e32 v100, v50, v18
	s_waitcnt lgkmcnt(0)
	v_fma_f32 v101, v49, v21, v142
	v_fmac_f32_e32 v101, v48, v20
	v_fmac_f32_e32 v101, v50, v22
	v_fmac_f32_e32 v100, v51, v19
	v_fmac_f32_e32 v101, v51, v23
	v_pk_fma_f32 v[52:53], v[46:47], v[32:33], v[36:37]
	v_pk_mul_f32 v[32:33], v[96:97], v[98:99] op_sel_hi:[1,0]
	ds_read_b128 v[94:97], v60 offset:3072
	v_pk_fma_f32 v[54:55], v[32:33], v[34:35], v[38:39]
	v_cvt_pk_bf16_f32 v32, v52, v53
	v_cvt_pk_bf16_f32 v33, v54, v55
	global_store_dwordx2 v[86:87], v[32:33], off offset:512
	ds_read_b128 v[32:35], v60 offset:7168
	s_waitcnt lgkmcnt(1)
	v_mul_f32_e32 v36, v53, v95
	v_fmac_f32_e32 v36, v52, v94
	v_fmac_f32_e32 v36, v54, v96
	v_fmac_f32_e32 v36, v55, v97
	v_add_f32_e32 v94, v42, v36
	ds_read_b128 v[36:39], v60 offset:11264
	ds_read_b128 v[130:133], v60 offset:15360
	s_waitcnt lgkmcnt(2)
	v_fma_f32 v95, v53, v33, v41
	v_fmac_f32_e32 v95, v52, v32
	v_fmac_f32_e32 v95, v54, v34
	s_waitcnt lgkmcnt(1)
	v_fma_f32 v96, v53, v37, v40
	v_fmac_f32_e32 v96, v52, v36
	v_fmac_f32_e32 v96, v54, v38
	v_fmac_f32_e32 v95, v55, v35
	v_fmac_f32_e32 v96, v55, v39
	ds_read_b128 v[40:43], v60 offset:19456
	s_waitcnt lgkmcnt(1)
	v_fma_f32 v97, v53, v131, v45
	v_fmac_f32_e32 v97, v52, v130
	v_fmac_f32_e32 v97, v54, v132
	v_fmac_f32_e32 v97, v55, v133
	ds_read_b128 v[130:133], v60 offset:23552
	s_waitcnt lgkmcnt(1)
	v_fma_f32 v125, v53, v41, v44
	v_fmac_f32_e32 v125, v52, v40
	v_fmac_f32_e32 v125, v54, v42
	v_fmac_f32_e32 v125, v55, v43
	ds_read_b128 v[134:137], v60 offset:27648
	s_waitcnt lgkmcnt(1)
	v_fma_f32 v124, v53, v131, v124
	v_fmac_f32_e32 v124, v52, v130
	v_fmac_f32_e32 v124, v54, v132
	v_fmac_f32_e32 v124, v55, v133
	ds_read_b128 v[130:133], v60 offset:31744
	s_waitcnt lgkmcnt(1)
	v_fma_f32 v98, v53, v135, v123
	v_fmac_f32_e32 v98, v52, v134
	v_fmac_f32_e32 v98, v54, v136
	v_fmac_f32_e32 v98, v55, v137
	ds_read_b128 v[134:137], v60 offset:35840
	s_waitcnt lgkmcnt(1)
	v_fma_f32 v122, v53, v131, v122
	v_fmac_f32_e32 v122, v52, v130
	v_fmac_f32_e32 v122, v54, v132
	v_fmac_f32_e32 v122, v55, v133
	ds_read_b128 v[130:133], v60 offset:39936
	s_waitcnt lgkmcnt(1)
	v_fma_f32 v111, v53, v135, v111
	v_fmac_f32_e32 v111, v52, v134
	v_fmac_f32_e32 v111, v54, v136
	v_fmac_f32_e32 v111, v55, v137
	ds_read_b128 v[134:137], v60 offset:44032
	s_waitcnt lgkmcnt(1)
	v_fma_f32 v110, v53, v131, v110
	v_fmac_f32_e32 v110, v52, v130
	v_fmac_f32_e32 v110, v54, v132
	v_fmac_f32_e32 v110, v55, v133
	ds_read_b128 v[130:133], v60 offset:48128
	s_waitcnt lgkmcnt(1)
	v_fma_f32 v109, v53, v135, v109
	v_fmac_f32_e32 v109, v52, v134
	v_fmac_f32_e32 v109, v54, v136
	v_fmac_f32_e32 v109, v55, v137
	ds_read_b128 v[134:137], v60 offset:52224
	s_waitcnt lgkmcnt(1)
	v_fma_f32 v108, v53, v131, v108
	v_fmac_f32_e32 v108, v52, v130
	v_fmac_f32_e32 v108, v54, v132
	v_fmac_f32_e32 v108, v55, v133
	ds_read_b128 v[130:133], v60 offset:56320
	s_waitcnt lgkmcnt(1)
	v_fma_f32 v103, v53, v135, v103
	v_fmac_f32_e32 v103, v52, v134
	v_fmac_f32_e32 v103, v54, v136
	v_fmac_f32_e32 v103, v55, v137
	ds_read_b128 v[134:137], v60 offset:60416
	s_waitcnt lgkmcnt(1)
	v_fma_f32 v102, v53, v131, v102
	v_fmac_f32_e32 v102, v52, v130
	v_fmac_f32_e32 v102, v54, v132
	v_fmac_f32_e32 v102, v55, v133
	ds_read_b128 v[130:133], v60 offset:64512
	s_waitcnt lgkmcnt(1)
	v_fma_f32 v123, v53, v135, v100
	v_fmac_f32_e32 v123, v52, v134
	v_fmac_f32_e32 v123, v54, v136
	v_fmac_f32_e32 v123, v55, v137
	s_waitcnt lgkmcnt(0)
	v_fma_f32 v129, v53, v131, v101
	v_fmac_f32_e32 v129, v52, v130
	v_fmac_f32_e32 v129, v54, v132
	v_fmac_f32_e32 v129, v55, v133
	v_mov_b32_e32 v100, v48
	v_mov_b32_e32 v101, v52
	v_mov_b32_e32 v52, v49
	v_mov_b32_e32 v48, v218
	v_mov_b32_e32 v126, v214
	v_mov_b32_e32 v130, v222
	v_mov_b32_e32 v127, v230
	v_mov_b32_e32 v49, v238
	v_pk_mul_f32 v[48:49], v[52:53], v[48:49]
	v_mov_b32_e32 v36, v219
	v_pk_fma_f32 v[48:49], v[100:101], v[126:127], v[48:49]
	v_mov_b32_e32 v126, v50
	v_mov_b32_e32 v127, v54
	v_mov_b32_e32 v131, v242
	v_pk_fma_f32 v[48:49], v[126:127], v[130:131], v[48:49]
	v_mov_b32_e32 v54, v51
	v_mov_b32_e32 v50, v226
	v_mov_b32_e32 v51, v246
	v_mov_b32_e32 v32, v215
	v_mov_b32_e32 v37, v239
	v_pk_mul_f32 v[24:25], v[52:53], v[36:37]
	v_pk_fma_f32 v[48:49], v[54:55], v[50:51], v[48:49]
	v_mov_b32_e32 v33, v231
	v_pk_fma_f32 v[24:25], v[100:101], v[32:33], v[24:25]
	v_mov_b32_e32 v40, v223
	v_add_f32_e32 v16, v107, v48
	v_mov_b32_e32 v41, v243
	v_pk_fma_f32 v[20:21], v[126:127], v[40:41], v[24:25]
	v_mov_b32_e32 v44, v227
	v_add_f32_e32 v28, v16, v49
	v_mov_b32_e32 v45, v247
	v_pk_fma_f32 v[16:17], v[54:55], v[44:45], v[20:21]
	v_mov_b32_e32 v20, v220
	v_add_f32_e32 v16, v105, v16
	v_mov_b32_e32 v21, v240
	v_add_f32_e32 v24, v16, v17
	v_mov_b32_e32 v16, v216
	v_mov_b32_e32 v17, v232
	v_pk_mul_f32 v[20:21], v[52:53], v[20:21]
	v_mov_b32_e32 v38, v221
	v_pk_fma_f32 v[16:17], v[100:101], v[16:17], v[20:21]
	v_mov_b32_e32 v20, v224
	v_mov_b32_e32 v21, v244
	v_pk_fma_f32 v[16:17], v[126:127], v[20:21], v[16:17]
	v_mov_b32_e32 v20, v228
	v_mov_b32_e32 v21, v248
	v_pk_fma_f32 v[16:17], v[54:55], v[20:21], v[16:17]
	v_mov_b32_e32 v34, v217
	v_add_f32_e32 v16, v106, v16
	v_add_f32_e32 v20, v16, v17
	v_mov_b32_e32 v39, v241
	v_pk_mul_f32 v[16:17], v[52:53], v[38:39]
	v_mov_b32_e32 v42, v225
	v_mov_b32_e32 v35, v233
	v_pk_fma_f32 v[16:17], v[100:101], v[34:35], v[16:17]
	v_mov_b32_e32 v46, v229
	v_mov_b32_e32 v43, v245
	v_pk_fma_f32 v[16:17], v[126:127], v[42:43], v[16:17]
	v_mov_b32_e32 v47, v249
	v_pk_fma_f32 v[16:17], v[54:55], v[46:47], v[16:17]
	v_add_f32_e32 v16, v104, v16
	v_add_f32_e32 v22, v16, v17
	v_add_f32_dpp v250, v24, v24 row_mirror row_mask:0xf bank_mask:0xf bound_ctrl:1
	v_add_f32_dpp v94, v94, v94 row_mirror row_mask:0xf bank_mask:0xf bound_ctrl:1
	v_add_f32_dpp v125, v125, v125 row_mirror row_mask:0xf bank_mask:0xf bound_ctrl:1
	v_add_f32_dpp v111, v111, v111 row_mirror row_mask:0xf bank_mask:0xf bound_ctrl:1
	v_add_f32_dpp v103, v103, v103 row_mirror row_mask:0xf bank_mask:0xf bound_ctrl:1
	v_add_f32_dpp v250, v20, v20 row_mirror row_mask:0xf bank_mask:0xc bound_ctrl:1
	v_add_f32_dpp v94, v95, v95 row_mirror row_mask:0xf bank_mask:0xc bound_ctrl:1
	v_add_f32_dpp v125, v124, v124 row_mirror row_mask:0xf bank_mask:0xc bound_ctrl:1
	v_add_f32_dpp v111, v110, v110 row_mirror row_mask:0xf bank_mask:0xc bound_ctrl:1
	v_add_f32_dpp v103, v102, v102 row_mirror row_mask:0xf bank_mask:0xc bound_ctrl:1
	v_add_f32_dpp v251, v28, v28 row_mirror row_mask:0xf bank_mask:0xf bound_ctrl:1
	v_add_f32_dpp v96, v96, v96 row_mirror row_mask:0xf bank_mask:0xf bound_ctrl:1
	v_add_f32_dpp v98, v98, v98 row_mirror row_mask:0xf bank_mask:0xf bound_ctrl:1
	v_add_f32_dpp v109, v109, v109 row_mirror row_mask:0xf bank_mask:0xf bound_ctrl:1
	v_add_f32_dpp v123, v123, v123 row_mirror row_mask:0xf bank_mask:0xf bound_ctrl:1
	v_add_f32_dpp v251, v22, v22 row_mirror row_mask:0xf bank_mask:0xc bound_ctrl:1
	v_add_f32_dpp v96, v97, v97 row_mirror row_mask:0xf bank_mask:0xc bound_ctrl:1
	v_add_f32_dpp v98, v122, v122 row_mirror row_mask:0xf bank_mask:0xc bound_ctrl:1
	v_add_f32_dpp v109, v108, v108 row_mirror row_mask:0xf bank_mask:0xc bound_ctrl:1
	v_add_f32_dpp v123, v129, v129 row_mirror row_mask:0xf bank_mask:0xc bound_ctrl:1
	v_add_f32_dpp v250, v250, v250 row_half_mirror row_mask:0xf bank_mask:0xf bound_ctrl:1
	v_add_f32_dpp v94, v94, v94 row_half_mirror row_mask:0xf bank_mask:0xf bound_ctrl:1
	v_add_f32_dpp v125, v125, v125 row_half_mirror row_mask:0xf bank_mask:0xf bound_ctrl:1
	v_add_f32_dpp v111, v111, v111 row_half_mirror row_mask:0xf bank_mask:0xf bound_ctrl:1
	v_add_f32_dpp v103, v103, v103 row_half_mirror row_mask:0xf bank_mask:0xf bound_ctrl:1
	v_add_f32_dpp v250, v251, v251 row_half_mirror row_mask:0xf bank_mask:0xa bound_ctrl:1
	v_add_f32_dpp v94, v96, v96 row_half_mirror row_mask:0xf bank_mask:0xa bound_ctrl:1
	v_add_f32_dpp v125, v98, v98 row_half_mirror row_mask:0xf bank_mask:0xa bound_ctrl:1
	v_add_f32_dpp v111, v109, v109 row_half_mirror row_mask:0xf bank_mask:0xa bound_ctrl:1
	v_add_f32_dpp v103, v123, v123 row_half_mirror row_mask:0xf bank_mask:0xa bound_ctrl:1
	v_add_f32_dpp v250, v250, v250 quad_perm:[1,0,3,2] row_mask:0xf bank_mask:0xf bound_ctrl:1
	v_add_f32_dpp v94, v94, v94 quad_perm:[1,0,3,2] row_mask:0xf bank_mask:0xf bound_ctrl:1
	v_add_f32_dpp v125, v125, v125 quad_perm:[1,0,3,2] row_mask:0xf bank_mask:0xf bound_ctrl:1
	v_add_f32_dpp v111, v111, v111 quad_perm:[1,0,3,2] row_mask:0xf bank_mask:0xf bound_ctrl:1
	v_add_f32_dpp v103, v103, v103 quad_perm:[1,0,3,2] row_mask:0xf bank_mask:0xf bound_ctrl:1
	v_add_f32_dpp v250, v250, v250 quad_perm:[2,3,0,1] row_mask:0xf bank_mask:0xf bound_ctrl:1
	v_add_f32_dpp v94, v94, v94 quad_perm:[2,3,0,1] row_mask:0xf bank_mask:0xf bound_ctrl:1
	v_add_f32_dpp v125, v125, v125 quad_perm:[2,3,0,1] row_mask:0xf bank_mask:0xf bound_ctrl:1
	v_add_f32_dpp v111, v111, v111 quad_perm:[2,3,0,1] row_mask:0xf bank_mask:0xf bound_ctrl:1
	v_add_f32_dpp v103, v103, v103 quad_perm:[2,3,0,1] row_mask:0xf bank_mask:0xf bound_ctrl:1
	v_readlane_b32 s2, v250, 20
	v_readlane_b32 s10, v250, 52
	v_readlane_b32 s0, v250, 4
	v_readlane_b32 s1, v250, 36
	v_mov_b32_e32 v16, s2
	v_mov_b32_e32 v17, s10
	v_readlane_b32 s2, v250, 16
	v_readlane_b32 s10, v250, 48
	v_pk_add_f32 v[16:17], s[0:1], v[16:17]
	v_readlane_b32 s0, v250, 0
	v_readlane_b32 s1, v250, 32
	v_mov_b32_e32 v18, s2
	v_mov_b32_e32 v19, s10
	v_readlane_b32 s2, v250, 24
	v_readlane_b32 s10, v250, 56
	v_pk_add_f32 v[18:19], s[0:1], v[18:19]
	v_readlane_b32 s0, v250, 8
	v_readlane_b32 s1, v250, 40
	v_mov_b32_e32 v20, s2
	v_mov_b32_e32 v21, s10
	v_pk_add_f32 v[20:21], s[0:1], v[20:21]
	v_mov_b32_e32 v25, v18
	v_add_f32_e32 v26, v20, v21
	v_mov_b32_e32 v18, v17
	v_readlane_b32 s2, v250, 28
	v_readlane_b32 s10, v250, 60
	v_readlane_b32 s0, v250, 12
	v_readlane_b32 s1, v250, 44
	v_mov_b32_e32 v20, s2
	v_mov_b32_e32 v21, s10
	v_pk_add_f32 v[20:21], s[0:1], v[20:21]
	v_add_f32_e32 v27, v20, v21
	v_readlane_b32 s14, v94, 0
	v_readlane_b32 s94, v94, 16
	v_readlane_b32 s15, v94, 32
	v_readlane_b32 s95, v94, 48
	v_readlane_b32 s87, v94, 8
	v_readlane_b32 s91, v94, 24
	v_readlane_b32 s90, v94, 40
	v_readlane_b32 s92, v94, 56
	v_readlane_b32 s65, v94, 4
	v_readlane_b32 s75, v94, 20
	v_readlane_b32 s66, v94, 36
	v_readlane_b32 s78, v94, 52
	v_readlane_b32 s51, v94, 12
	v_readlane_b32 s53, v94, 28
	v_readlane_b32 s52, v94, 44
	v_readlane_b32 s54, v94, 60
	v_readlane_b32 s35, v125, 0
	v_readlane_b32 s37, v125, 16
	v_readlane_b32 s36, v125, 32
	v_readlane_b32 s38, v125, 48
	v_readlane_b32 s23, v125, 8
	v_readlane_b32 s27, v125, 24
	v_readlane_b32 s26, v125, 40
	v_readlane_b32 s93, v125, 56
	v_readlane_b32 s81, v125, 4
	v_readlane_b32 s83, v125, 20
	v_readlane_b32 s82, v125, 36
	v_readlane_b32 s84, v125, 52
	v_readlane_b32 s63, v125, 12
	v_readlane_b32 s67, v125, 28
	v_readlane_b32 s64, v125, 44
	v_readlane_b32 s70, v125, 60
	v_readlane_b32 s59, v111, 0
	v_readlane_b32 s61, v111, 16
	v_readlane_b32 s60, v111, 32
	v_readlane_b32 s62, v111, 48
	v_readlane_b32 s55, v111, 8
	v_readlane_b32 s57, v111, 24
	v_readlane_b32 s56, v111, 40
	v_readlane_b32 s58, v111, 56
	v_readlane_b32 s47, v111, 4
	v_readlane_b32 s49, v111, 20
	v_readlane_b32 s48, v111, 36
	v_readlane_b32 s50, v111, 52
	v_readlane_b32 s43, v111, 12
	v_readlane_b32 s45, v111, 28
	v_readlane_b32 s44, v111, 44
	v_readlane_b32 s46, v111, 60
	v_readlane_b32 s39, v103, 0
	v_readlane_b32 s41, v103, 16
	v_readlane_b32 s40, v103, 32
	v_readlane_b32 s42, v103, 48
	v_readlane_b32 s30, v103, 8
	v_readlane_b32 s33, v103, 24
	v_readlane_b32 s31, v103, 40
	v_readlane_b32 s34, v103, 56
	v_readlane_b32 s28, v103, 4
	v_readlane_b32 s29, v103, 20
	v_readlane_b32 s85, v103, 36
	v_readlane_b32 s86, v103, 52
	v_mov_b32_e32 v24, v16
	v_pk_add_f32 v[16:17], v[24:25], v[18:19]
	v_mov_b32_e32 v20, v178
	v_mov_b32_e32 v21, v179
	v_mov_b32_e32 v22, v180
	v_mov_b32_e32 v23, v181
	v_add_f32_e32 v19, v26, v22
	v_pk_add_f32 v[16:17], v[16:17], v[20:21]
	v_add_f32_e32 v18, v27, v23
	v_cmp_gt_f32_e32 vcc, v17, v16
	v_mov_b32_e32 v22, 0
	v_readlane_b32 s71, v103, 12
	v_cndmask_b32_e32 v20, v16, v17, vcc
	v_cmp_gt_f32_e64 s[12:13], v19, v20
	v_cndmask_b32_e64 v21, 0, 1, vcc
	s_and_b64 s[10:11], s[12:13], exec
	v_cndmask_b32_e64 v20, v20, v19, s[12:13]
	v_cmp_ngt_f32_e64 s[0:1], v18, v20
	v_readfirstlane_b32 s2, v21
	s_cselect_b32 s2, 2, s2
	s_and_b64 s[10:11], s[0:1], exec
	s_cselect_b32 s2, s2, 3
	s_cmp_eq_u32 s2, 0
	s_cselect_b64 s[24:25], -1, 0
	s_cmp_lg_u32 s2, 0
	v_mov_b32_e32 v21, 0
	v_readlane_b32 s79, v103, 28
	v_readlane_b32 s74, v103, 44
	v_readlane_b32 s80, v103, 60
	v_cmp_gt_f32_e64 s[10:11], v18, v20
	s_waitcnt lgkmcnt(0)
	s_cbranch_scc0 .LBB0_1684
	v_cndmask_b32_e64 v23, 0, 1, s[24:25]
	v_cmp_ne_u32_e64 s[14:15], 1, v23
	s_andn2_b64 vcc, exec, s[24:25]
	s_cbranch_vccz .LBB0_1685
